# P0 w_in transpose/convert loop hand-written: all four items' loads (32 x dwordx4 per wave) issued up front
# baseline (speedup 1.0000x reference)
.LBB0_7:
	v_writelane_b32 v242, s4, 11
	s_load_dwordx16 s[4:19], s[0:1], 0x40
	s_lshr_b32 s1, s3, 6
	s_lshl_b32 s0, s2, 3
	s_add_i32 s56, s1, s0
	s_lshl_b32 s64, s74, 3
	s_waitcnt lgkmcnt(0)
	v_writelane_b32 v242, s4, 12
	v_and_b32_e32 v142, 63, v143
	s_nop 0
	v_writelane_b32 v242, s5, 13
	v_writelane_b32 v242, s6, 14
	v_writelane_b32 v242, s7, 15
	v_writelane_b32 v242, s8, 16
	v_writelane_b32 v242, s9, 17
	v_writelane_b32 v242, s10, 18
	v_writelane_b32 v242, s11, 19
	v_writelane_b32 v242, s12, 20
	v_writelane_b32 v242, s13, 21
	v_writelane_b32 v242, s14, 22
	v_writelane_b32 v242, s15, 23
	v_writelane_b32 v242, s16, 24
	v_writelane_b32 v242, s17, 25
	v_writelane_b32 v242, s18, 26
	v_writelane_b32 v242, s19, 27
	s_add_u32 s6, s70, 0x100000
	s_addc_u32 s7, s71, 0
	s_lshl_b32 s0, s1, 14
	v_writelane_b32 v242, s1, 28
	s_add_i32 s0, s0, 0
	v_writelane_b32 v242, s0, 29
	v_writelane_b32 v242, s65, 30
	v_writelane_b32 v242, s36, 31
	s_cmp_lt_i32 s72, 1
	s_cselect_b64 s[0:1], -1, 0
	v_writelane_b32 v242, s37, 32
	v_writelane_b32 v242, s38, 33
	v_writelane_b32 v242, s39, 34
	v_writelane_b32 v242, s40, 35
	v_writelane_b32 v242, s41, 36
	v_writelane_b32 v242, s42, 37
	v_writelane_b32 v242, s43, 38
	v_writelane_b32 v242, s44, 39
	v_writelane_b32 v242, s45, 40
	v_writelane_b32 v242, s46, 41
	s_cmp_gt_i32 s73, 0
	v_writelane_b32 v242, s47, 42
	s_cselect_b64 s[4:5], -1, 0
	v_writelane_b32 v242, s48, 43
	s_and_b64 s[4:5], s[0:1], s[4:5]
	v_writelane_b32 v242, s49, 44
	s_andn2_b64 vcc, exec, s[4:5]
	v_writelane_b32 v242, s50, 45
	v_writelane_b32 v242, s51, 46
	s_cbranch_vccnz .LBB0_22
	v_lshrrev_b32_e32 v2, 3, v142
	v_and_b32_e32 v3, 7, v142
	s_lshr_b32 s3, s56, 8
	s_and_b32 s8, s56, 0xff
	v_readlane_b32 s10, v242, 14
	v_readlane_b32 s11, v242, 15
	v_readlane_b32 s9, v242, 29
	v_lshlrev_b32_e32 v6, 15, v2
	v_lshlrev_b32_e32 v8, 4, v3
	v_mov_b32_e32 v9, 0
	v_add_u32_e32 v6, v6, v8
	s_lshl_b32 s0, s8, 7
	s_lshl_b32 s12, s3, 21
	s_add_u32 s0, s0, s12
	s_add_u32 s0, s10, s0
	s_addc_u32 s1, s11, 0
	global_load_dwordx4 v[100:103], v6, s[0:1]
	s_add_u32 s14, s0, 0x40000
	s_addc_u32 s15, s1, 0
	global_load_dwordx4 v[104:107], v6, s[14:15]
	s_add_u32 s0, s14, 0x40000
	s_addc_u32 s1, s15, 0
	global_load_dwordx4 v[108:111], v6, s[0:1]
	s_add_u32 s14, s0, 0x40000
	s_addc_u32 s15, s1, 0
	global_load_dwordx4 v[112:115], v6, s[14:15]
	s_add_u32 s0, s14, 0x40000
	s_addc_u32 s1, s15, 0
	global_load_dwordx4 v[116:119], v6, s[0:1]
	s_add_u32 s14, s0, 0x40000
	s_addc_u32 s15, s1, 0
	global_load_dwordx4 v[120:123], v6, s[14:15]
	s_add_u32 s0, s14, 0x40000
	s_addc_u32 s1, s15, 0
	global_load_dwordx4 v[124:127], v6, s[0:1]
	s_add_u32 s14, s0, 0x40000
	s_addc_u32 s15, s1, 0
	global_load_dwordx4 v[128:131], v6, s[14:15]
	s_add_u32 s0, s14, 0xe40000
	s_addc_u32 s1, s15, 0
	global_load_dwordx4 v[132:135], v6, s[0:1]
	s_add_u32 s14, s0, 0x40000
	s_addc_u32 s15, s1, 0
	global_load_dwordx4 v[136:139], v6, s[14:15]
	s_add_u32 s0, s14, 0x40000
	s_addc_u32 s1, s15, 0
	global_load_dwordx4 v[144:147], v6, s[0:1]
	s_add_u32 s14, s0, 0x40000
	s_addc_u32 s15, s1, 0
	global_load_dwordx4 v[148:151], v6, s[14:15]
	s_add_u32 s0, s14, 0x40000
	s_addc_u32 s1, s15, 0
	global_load_dwordx4 v[152:155], v6, s[0:1]
	s_add_u32 s14, s0, 0x40000
	s_addc_u32 s15, s1, 0
	global_load_dwordx4 v[156:159], v6, s[14:15]
	s_add_u32 s0, s14, 0x40000
	s_addc_u32 s1, s15, 0
	global_load_dwordx4 v[160:163], v6, s[0:1]
	s_add_u32 s14, s0, 0x40000
	s_addc_u32 s15, s1, 0
	global_load_dwordx4 v[164:167], v6, s[14:15]
	s_add_u32 s0, s14, 0xe40000
	s_addc_u32 s1, s15, 0
	global_load_dwordx4 v[168:171], v6, s[0:1]
	s_add_u32 s14, s0, 0x40000
	s_addc_u32 s15, s1, 0
	global_load_dwordx4 v[172:175], v6, s[14:15]
	s_add_u32 s0, s14, 0x40000
	s_addc_u32 s1, s15, 0
	global_load_dwordx4 v[176:179], v6, s[0:1]
	s_add_u32 s14, s0, 0x40000
	s_addc_u32 s15, s1, 0
	global_load_dwordx4 v[180:183], v6, s[14:15]
	s_add_u32 s0, s14, 0x40000
	s_addc_u32 s1, s15, 0
	global_load_dwordx4 v[184:187], v6, s[0:1]
	s_add_u32 s14, s0, 0x40000
	s_addc_u32 s15, s1, 0
	global_load_dwordx4 v[188:191], v6, s[14:15]
	s_add_u32 s0, s14, 0x40000
	s_addc_u32 s1, s15, 0
	global_load_dwordx4 v[192:195], v6, s[0:1]
	s_add_u32 s14, s0, 0x40000
	s_addc_u32 s15, s1, 0
	global_load_dwordx4 v[196:199], v6, s[14:15]
	s_add_u32 s0, s14, 0xe40000
	s_addc_u32 s1, s15, 0
	global_load_dwordx4 v[200:203], v6, s[0:1]
	s_add_u32 s14, s0, 0x40000
	s_addc_u32 s15, s1, 0
	global_load_dwordx4 v[204:207], v6, s[14:15]
	s_add_u32 s0, s14, 0x40000
	s_addc_u32 s1, s15, 0
	global_load_dwordx4 v[208:211], v6, s[0:1]
	s_add_u32 s14, s0, 0x40000
	s_addc_u32 s15, s1, 0
	global_load_dwordx4 v[212:215], v6, s[14:15]
	s_add_u32 s0, s14, 0x40000
	s_addc_u32 s1, s15, 0
	global_load_dwordx4 v[216:219], v6, s[0:1]
	s_add_u32 s14, s0, 0x40000
	s_addc_u32 s15, s1, 0
	global_load_dwordx4 v[220:223], v6, s[14:15]
	s_add_u32 s0, s14, 0x40000
	s_addc_u32 s1, s15, 0
	global_load_dwordx4 v[224:227], v6, s[0:1]
	s_add_u32 s14, s0, 0x40000
	s_addc_u32 s15, s1, 0
	global_load_dwordx4 v[228:231], v6, s[14:15]
	v_mul_u32_u24_e32 v10, 0x84, v2
	v_lshl_add_u32 v10, v3, 4, v10
	v_add_u32_e32 v10, s9, v10
	v_add_u32_e32 v11, 0x420, v10
	v_add_u32_e32 v12, 0x840, v10
	v_add_u32_e32 v13, 0xc60, v10
	v_add_u32_e32 v14, 0x1080, v10
	v_add_u32_e32 v15, 0x14a0, v10
	v_add_u32_e32 v16, 0x18c0, v10
	v_add_u32_e32 v17, 0x1ce0, v10
	v_mul_u32_u24_e32 v18, 0x420, v3
	v_lshl_add_u32 v18, v2, 2, v18
	v_add_u32_e32 v18, s9, v18
	s_lshl_b32 s16, s8, 5
	v_add_u32_e32 v28, s16, v2
	v_mov_b32_e32 v29, 0
	v_lshlrev_b64 v[28:29], 12, v[28:29]
	s_lshl_b32 s16, s3, 7
	s_add_u32 s16, s6, s16
	s_addc_u32 s17, s7, 0
	v_lshl_add_u64 v[20:21], v[28:29], 0, s[16:17]
	v_lshl_add_u64 v[20:21], v[20:21], 0, v[8:9]
	s_mov_b64 s[18:19], 0x8000
	v_lshl_add_u64 v[22:23], v[20:21], 0, s[18:19]
	v_lshl_add_u64 v[24:25], v[22:23], 0, s[18:19]
	v_lshl_add_u64 v[26:27], v[24:25], 0, s[18:19]
	s_waitcnt vmcnt(31)
	ds_write2_b32 v10, v100, v101 offset1:1
	ds_write2_b32 v10, v102, v103 offset0:2 offset1:3
	s_waitcnt vmcnt(30)
	ds_write2_b32 v11, v104, v105 offset1:1
	ds_write2_b32 v11, v106, v107 offset0:2 offset1:3
	s_waitcnt vmcnt(29)
	ds_write2_b32 v12, v108, v109 offset1:1
	ds_write2_b32 v12, v110, v111 offset0:2 offset1:3
	s_waitcnt vmcnt(28)
	ds_write2_b32 v13, v112, v113 offset1:1
	ds_write2_b32 v13, v114, v115 offset0:2 offset1:3
	s_waitcnt vmcnt(27)
	ds_write2_b32 v14, v116, v117 offset1:1
	ds_write2_b32 v14, v118, v119 offset0:2 offset1:3
	s_waitcnt vmcnt(26)
	ds_write2_b32 v15, v120, v121 offset1:1
	ds_write2_b32 v15, v122, v123 offset0:2 offset1:3
	s_waitcnt vmcnt(25)
	ds_write2_b32 v16, v124, v125 offset1:1
	ds_write2_b32 v16, v126, v127 offset0:2 offset1:3
	s_waitcnt vmcnt(24)
	ds_write2_b32 v17, v128, v129 offset1:1
	ds_write2_b32 v17, v130, v131 offset0:2 offset1:3
	s_waitcnt lgkmcnt(0)
	ds_read2_b32 v[44:45], v18 offset0:0 offset1:8
	ds_read2_b32 v[46:47], v18 offset0:33 offset1:41
	ds_read2_b32 v[48:49], v18 offset0:66 offset1:74
	ds_read2_b32 v[50:51], v18 offset0:99 offset1:107
	ds_read2_b32 v[52:53], v18 offset0:132 offset1:140
	ds_read2_b32 v[54:55], v18 offset0:165 offset1:173
	ds_read2_b32 v[56:57], v18 offset0:198 offset1:206
	ds_read2_b32 v[58:59], v18 offset0:231 offset1:239
	ds_read2_b32 v[60:61], v18 offset0:16 offset1:24
	ds_read2_b32 v[62:63], v18 offset0:49 offset1:57
	ds_read2_b32 v[64:65], v18 offset0:82 offset1:90
	ds_read2_b32 v[66:67], v18 offset0:115 offset1:123
	ds_read2_b32 v[68:69], v18 offset0:148 offset1:156
	ds_read2_b32 v[70:71], v18 offset0:181 offset1:189
	ds_read2_b32 v[72:73], v18 offset0:214 offset1:222
	ds_read2_b32 v[74:75], v18 offset0:247 offset1:255
	s_waitcnt lgkmcnt(8)
	v_cvt_pk_bf16_f32 v76, v44, v46
	v_cvt_pk_bf16_f32 v77, v48, v50
	v_cvt_pk_bf16_f32 v78, v52, v54
	v_cvt_pk_bf16_f32 v79, v56, v58
	global_store_dwordx4 v[20:21], v[76:79], off
	v_cvt_pk_bf16_f32 v80, v45, v47
	v_cvt_pk_bf16_f32 v81, v49, v51
	v_cvt_pk_bf16_f32 v82, v53, v55
	v_cvt_pk_bf16_f32 v83, v57, v59
	global_store_dwordx4 v[22:23], v[80:83], off
	s_waitcnt lgkmcnt(0)
	v_cvt_pk_bf16_f32 v84, v60, v62
	v_cvt_pk_bf16_f32 v85, v64, v66
	v_cvt_pk_bf16_f32 v86, v68, v70
	v_cvt_pk_bf16_f32 v87, v72, v74
	global_store_dwordx4 v[24:25], v[84:87], off
	v_cvt_pk_bf16_f32 v88, v61, v63
	v_cvt_pk_bf16_f32 v89, v65, v67
	v_cvt_pk_bf16_f32 v90, v69, v71
	v_cvt_pk_bf16_f32 v91, v73, v75
	global_store_dwordx4 v[26:27], v[88:91], off
	s_waitcnt vmcnt(27)
	ds_write2_b32 v10, v132, v133 offset1:1
	ds_write2_b32 v10, v134, v135 offset0:2 offset1:3
	s_waitcnt vmcnt(26)
	ds_write2_b32 v11, v136, v137 offset1:1
	ds_write2_b32 v11, v138, v139 offset0:2 offset1:3
	s_waitcnt vmcnt(25)
	ds_write2_b32 v12, v144, v145 offset1:1
	ds_write2_b32 v12, v146, v147 offset0:2 offset1:3
	s_waitcnt vmcnt(24)
	ds_write2_b32 v13, v148, v149 offset1:1
	ds_write2_b32 v13, v150, v151 offset0:2 offset1:3
	s_waitcnt vmcnt(23)
	ds_write2_b32 v14, v152, v153 offset1:1
	ds_write2_b32 v14, v154, v155 offset0:2 offset1:3
	s_waitcnt vmcnt(22)
	ds_write2_b32 v15, v156, v157 offset1:1
	ds_write2_b32 v15, v158, v159 offset0:2 offset1:3
	s_waitcnt vmcnt(21)
	ds_write2_b32 v16, v160, v161 offset1:1
	ds_write2_b32 v16, v162, v163 offset0:2 offset1:3
	s_waitcnt vmcnt(20)
	ds_write2_b32 v17, v164, v165 offset1:1
	ds_write2_b32 v17, v166, v167 offset0:2 offset1:3
	s_waitcnt lgkmcnt(0)
	ds_read2_b32 v[44:45], v18 offset0:0 offset1:8
	ds_read2_b32 v[46:47], v18 offset0:33 offset1:41
	ds_read2_b32 v[48:49], v18 offset0:66 offset1:74
	ds_read2_b32 v[50:51], v18 offset0:99 offset1:107
	ds_read2_b32 v[52:53], v18 offset0:132 offset1:140
	ds_read2_b32 v[54:55], v18 offset0:165 offset1:173
	ds_read2_b32 v[56:57], v18 offset0:198 offset1:206
	ds_read2_b32 v[58:59], v18 offset0:231 offset1:239
	ds_read2_b32 v[60:61], v18 offset0:16 offset1:24
	ds_read2_b32 v[62:63], v18 offset0:49 offset1:57
	ds_read2_b32 v[64:65], v18 offset0:82 offset1:90
	ds_read2_b32 v[66:67], v18 offset0:115 offset1:123
	ds_read2_b32 v[68:69], v18 offset0:148 offset1:156
	ds_read2_b32 v[70:71], v18 offset0:181 offset1:189
	ds_read2_b32 v[72:73], v18 offset0:214 offset1:222
	ds_read2_b32 v[74:75], v18 offset0:247 offset1:255
	s_waitcnt lgkmcnt(8)
	v_cvt_pk_bf16_f32 v76, v44, v46
	v_cvt_pk_bf16_f32 v77, v48, v50
	v_cvt_pk_bf16_f32 v78, v52, v54
	v_cvt_pk_bf16_f32 v79, v56, v58
	global_store_dwordx4 v[20:21], v[76:79], off offset:1024
	v_cvt_pk_bf16_f32 v80, v45, v47
	v_cvt_pk_bf16_f32 v81, v49, v51
	v_cvt_pk_bf16_f32 v82, v53, v55
	v_cvt_pk_bf16_f32 v83, v57, v59
	global_store_dwordx4 v[22:23], v[80:83], off offset:1024
	s_waitcnt lgkmcnt(0)
	v_cvt_pk_bf16_f32 v84, v60, v62
	v_cvt_pk_bf16_f32 v85, v64, v66
	v_cvt_pk_bf16_f32 v86, v68, v70
	v_cvt_pk_bf16_f32 v87, v72, v74
	global_store_dwordx4 v[24:25], v[84:87], off offset:1024
	v_cvt_pk_bf16_f32 v88, v61, v63
	v_cvt_pk_bf16_f32 v89, v65, v67
	v_cvt_pk_bf16_f32 v90, v69, v71
	v_cvt_pk_bf16_f32 v91, v73, v75
	global_store_dwordx4 v[26:27], v[88:91], off offset:1024
	s_waitcnt vmcnt(23)
	ds_write2_b32 v10, v168, v169 offset1:1
	ds_write2_b32 v10, v170, v171 offset0:2 offset1:3
	s_waitcnt vmcnt(22)
	ds_write2_b32 v11, v172, v173 offset1:1
	ds_write2_b32 v11, v174, v175 offset0:2 offset1:3
	s_waitcnt vmcnt(21)
	ds_write2_b32 v12, v176, v177 offset1:1
	ds_write2_b32 v12, v178, v179 offset0:2 offset1:3
	s_waitcnt vmcnt(20)
	ds_write2_b32 v13, v180, v181 offset1:1
	ds_write2_b32 v13, v182, v183 offset0:2 offset1:3
	s_waitcnt vmcnt(19)
	ds_write2_b32 v14, v184, v185 offset1:1
	ds_write2_b32 v14, v186, v187 offset0:2 offset1:3
	s_waitcnt vmcnt(18)
	ds_write2_b32 v15, v188, v189 offset1:1
	ds_write2_b32 v15, v190, v191 offset0:2 offset1:3
	s_waitcnt vmcnt(17)
	ds_write2_b32 v16, v192, v193 offset1:1
	ds_write2_b32 v16, v194, v195 offset0:2 offset1:3
	s_waitcnt vmcnt(16)
	ds_write2_b32 v17, v196, v197 offset1:1
	ds_write2_b32 v17, v198, v199 offset0:2 offset1:3
	s_waitcnt lgkmcnt(0)
	ds_read2_b32 v[44:45], v18 offset0:0 offset1:8
	ds_read2_b32 v[46:47], v18 offset0:33 offset1:41
	ds_read2_b32 v[48:49], v18 offset0:66 offset1:74
	ds_read2_b32 v[50:51], v18 offset0:99 offset1:107
	ds_read2_b32 v[52:53], v18 offset0:132 offset1:140
	ds_read2_b32 v[54:55], v18 offset0:165 offset1:173
	ds_read2_b32 v[56:57], v18 offset0:198 offset1:206
	ds_read2_b32 v[58:59], v18 offset0:231 offset1:239
	ds_read2_b32 v[60:61], v18 offset0:16 offset1:24
	ds_read2_b32 v[62:63], v18 offset0:49 offset1:57
	ds_read2_b32 v[64:65], v18 offset0:82 offset1:90
	ds_read2_b32 v[66:67], v18 offset0:115 offset1:123
	ds_read2_b32 v[68:69], v18 offset0:148 offset1:156
	ds_read2_b32 v[70:71], v18 offset0:181 offset1:189
	ds_read2_b32 v[72:73], v18 offset0:214 offset1:222
	ds_read2_b32 v[74:75], v18 offset0:247 offset1:255
	s_waitcnt lgkmcnt(8)
	v_cvt_pk_bf16_f32 v76, v44, v46
	v_cvt_pk_bf16_f32 v77, v48, v50
	v_cvt_pk_bf16_f32 v78, v52, v54
	v_cvt_pk_bf16_f32 v79, v56, v58
	global_store_dwordx4 v[20:21], v[76:79], off offset:2048
	v_cvt_pk_bf16_f32 v80, v45, v47
	v_cvt_pk_bf16_f32 v81, v49, v51
	v_cvt_pk_bf16_f32 v82, v53, v55
	v_cvt_pk_bf16_f32 v83, v57, v59
	global_store_dwordx4 v[22:23], v[80:83], off offset:2048
	s_waitcnt lgkmcnt(0)
	v_cvt_pk_bf16_f32 v84, v60, v62
	v_cvt_pk_bf16_f32 v85, v64, v66
	v_cvt_pk_bf16_f32 v86, v68, v70
	v_cvt_pk_bf16_f32 v87, v72, v74
	global_store_dwordx4 v[24:25], v[84:87], off offset:2048
	v_cvt_pk_bf16_f32 v88, v61, v63
	v_cvt_pk_bf16_f32 v89, v65, v67
	v_cvt_pk_bf16_f32 v90, v69, v71
	v_cvt_pk_bf16_f32 v91, v73, v75
	global_store_dwordx4 v[26:27], v[88:91], off offset:2048
	s_waitcnt vmcnt(19)
	ds_write2_b32 v10, v200, v201 offset1:1
	ds_write2_b32 v10, v202, v203 offset0:2 offset1:3
	s_waitcnt vmcnt(18)
	ds_write2_b32 v11, v204, v205 offset1:1
	ds_write2_b32 v11, v206, v207 offset0:2 offset1:3
	s_waitcnt vmcnt(17)
	ds_write2_b32 v12, v208, v209 offset1:1
	ds_write2_b32 v12, v210, v211 offset0:2 offset1:3
	s_waitcnt vmcnt(16)
	ds_write2_b32 v13, v212, v213 offset1:1
	ds_write2_b32 v13, v214, v215 offset0:2 offset1:3
	s_waitcnt vmcnt(15)
	ds_write2_b32 v14, v216, v217 offset1:1
	ds_write2_b32 v14, v218, v219 offset0:2 offset1:3
	s_waitcnt vmcnt(14)
	ds_write2_b32 v15, v220, v221 offset1:1
	ds_write2_b32 v15, v222, v223 offset0:2 offset1:3
	s_waitcnt vmcnt(13)
	ds_write2_b32 v16, v224, v225 offset1:1
	ds_write2_b32 v16, v226, v227 offset0:2 offset1:3
	s_waitcnt vmcnt(12)
	ds_write2_b32 v17, v228, v229 offset1:1
	ds_write2_b32 v17, v230, v231 offset0:2 offset1:3
	s_waitcnt lgkmcnt(0)
	ds_read2_b32 v[44:45], v18 offset0:0 offset1:8
	ds_read2_b32 v[46:47], v18 offset0:33 offset1:41
	ds_read2_b32 v[48:49], v18 offset0:66 offset1:74
	ds_read2_b32 v[50:51], v18 offset0:99 offset1:107
	ds_read2_b32 v[52:53], v18 offset0:132 offset1:140
	ds_read2_b32 v[54:55], v18 offset0:165 offset1:173
	ds_read2_b32 v[56:57], v18 offset0:198 offset1:206
	ds_read2_b32 v[58:59], v18 offset0:231 offset1:239
	ds_read2_b32 v[60:61], v18 offset0:16 offset1:24
	ds_read2_b32 v[62:63], v18 offset0:49 offset1:57
	ds_read2_b32 v[64:65], v18 offset0:82 offset1:90
	ds_read2_b32 v[66:67], v18 offset0:115 offset1:123
	ds_read2_b32 v[68:69], v18 offset0:148 offset1:156
	ds_read2_b32 v[70:71], v18 offset0:181 offset1:189
	ds_read2_b32 v[72:73], v18 offset0:214 offset1:222
	ds_read2_b32 v[74:75], v18 offset0:247 offset1:255
	s_waitcnt lgkmcnt(8)
	v_cvt_pk_bf16_f32 v76, v44, v46
	v_cvt_pk_bf16_f32 v77, v48, v50
	v_cvt_pk_bf16_f32 v78, v52, v54
	v_cvt_pk_bf16_f32 v79, v56, v58
	global_store_dwordx4 v[20:21], v[76:79], off offset:3072
	v_cvt_pk_bf16_f32 v80, v45, v47
	v_cvt_pk_bf16_f32 v81, v49, v51
	v_cvt_pk_bf16_f32 v82, v53, v55
	v_cvt_pk_bf16_f32 v83, v57, v59
	global_store_dwordx4 v[22:23], v[80:83], off offset:3072
	s_waitcnt lgkmcnt(0)
	v_cvt_pk_bf16_f32 v84, v60, v62
	v_cvt_pk_bf16_f32 v85, v64, v66
	v_cvt_pk_bf16_f32 v86, v68, v70
	v_cvt_pk_bf16_f32 v87, v72, v74
	global_store_dwordx4 v[24:25], v[84:87], off offset:3072
	v_cvt_pk_bf16_f32 v88, v61, v63
	v_cvt_pk_bf16_f32 v89, v65, v67
	v_cvt_pk_bf16_f32 v90, v69, v71
	v_cvt_pk_bf16_f32 v91, v73, v75
	global_store_dwordx4 v[26:27], v[88:91], off offset:3072
